# flash loops: hipcc's two-branch wave-uniform interior-tile test between exp block and PV MFMAs collapsed to one branch (41 sites)
# speedup vs baseline: 1.0059x; 1.0059x over previous
.LBB0_497:
	v_cvt_pk_bf16_f32 v0, v0, v1
	v_cvt_pk_bf16_f32 v1, v2, v3
	v_cvt_pk_bf16_f32 v2, v4, v5
	v_cvt_pk_bf16_f32 v3, v6, v7
	s_add_i32 s2, s66, 0xffffff1f
	s_cmp_gt_i32 s2, s76
	v_mfma_f32_16x16x32_bf16 v[36:39], v[32:35], v[0:3], v[50:53]
	ds_read_b128 v[0:3], v44 offset:8192
	ds_read_b128 v[4:7], v45 offset:8192
	s_nop 0
	ds_read_b128 v[48:51], v44 offset:10240
	ds_read_b128 v[52:55], v45 offset:10240
	s_mov_b64 s[70:71], -1
	s_waitcnt lgkmcnt(3)
	v_mfma_f32_16x16x32_bf16 v[0:3], v[0:3], v[24:27], 0
	s_waitcnt lgkmcnt(2)
	v_mfma_f32_16x16x32_bf16 v[0:3], v[4:7], v[28:31], v[0:3]
	s_waitcnt lgkmcnt(1)
	v_mfma_f32_16x16x32_bf16 v[4:7], v[48:51], v[24:27], 0
	s_waitcnt lgkmcnt(0)
	v_mfma_f32_16x16x32_bf16 v[4:7], v[52:55], v[28:31], v[4:7]
	s_nop 3
	v_fma_f32 v0, v0, s30, 0
	v_fma_f32 v1, v1, s30, 0
	v_fma_f32 v2, v2, s30, 0
	v_fma_f32 v3, v3, s30, 0
	v_exp_f32_e32 v0, v0
	v_fma_f32 v4, v4, s30, 0
	v_fma_f32 v5, v5, s30, 0
	v_fma_f32 v6, v6, s30, 0
	v_fma_f32 v7, v7, s30, 0
	v_exp_f32_e32 v1, v1
	v_exp_f32_e32 v2, v2
	v_exp_f32_e32 v3, v3
	v_exp_f32_e32 v4, v4
	v_exp_f32_e32 v5, v5
	v_exp_f32_e32 v6, v6
	v_exp_f32_e32 v7, v7
	s_cbranch_scc0 .LBB0_501
.LBB0_499:
	v_add_u32_e32 v47, 0xffffff00, v46
	s_nop 0
	v_cmp_gt_i32_e32 vcc, 1, v47
	s_nop 1
	v_cndmask_b32_e32 v0, 0, v0, vcc
	v_cmp_gt_i32_e32 vcc, 0, v47
	s_nop 1
	v_cndmask_b32_e32 v1, 0, v1, vcc
	v_cmp_gt_i32_e32 vcc, -1, v47
	s_nop 1
	v_cndmask_b32_e32 v2, 0, v2, vcc
	v_cmp_gt_i32_e32 vcc, -2, v47
	s_nop 1
	v_cndmask_b32_e32 v3, 0, v3, vcc
	v_cmp_gt_i32_e32 vcc, -15, v47
	s_nop 1
	v_cndmask_b32_e32 v4, 0, v4, vcc
	v_cmp_gt_i32_e32 vcc, -16, v47
	s_nop 1
	v_cndmask_b32_e32 v5, 0, v5, vcc
	v_cmp_gt_i32_e32 vcc, s14, v47
	s_nop 1
	v_cndmask_b32_e32 v6, 0, v6, vcc
	v_cmp_gt_i32_e32 vcc, s15, v47
	s_nop 1
	v_cndmask_b32_e32 v7, 0, v7, vcc

.LBB0_506:
	ds_read_b128 v[0:3], v44 offset:16384
	ds_read_b128 v[4:7], v44 offset:18432
	ds_read_b128 v[36:39], v45 offset:16384
	s_add_i32 s2, s66, 0xffffff3f
	s_cmp_gt_i32 s2, s76
	s_mov_b64 s[68:69], -1
	s_waitcnt lgkmcnt(2)
	v_mfma_f32_16x16x32_bf16 v[0:3], v[0:3], v[24:27], 0
	s_waitcnt lgkmcnt(0)
	v_mfma_f32_16x16x32_bf16 v[0:3], v[36:39], v[28:31], v[0:3]
	ds_read_b128 v[36:39], v45 offset:18432
	v_mfma_f32_16x16x32_bf16 v[4:7], v[4:7], v[24:27], 0
	s_waitcnt lgkmcnt(0)
	v_mfma_f32_16x16x32_bf16 v[4:7], v[36:39], v[28:31], v[4:7]
	s_nop 3
	v_fma_f32 v0, v0, s30, 0
	v_fma_f32 v1, v1, s30, 0
	v_fma_f32 v2, v2, s30, 0
	v_fma_f32 v3, v3, s30, 0
	v_fma_f32 v4, v4, s30, 0
	v_fma_f32 v5, v5, s30, 0
	v_fma_f32 v6, v6, s30, 0
	v_fma_f32 v7, v7, s30, 0
	v_exp_f32_e32 v0, v0
	v_exp_f32_e32 v1, v1
	v_exp_f32_e32 v2, v2
	v_exp_f32_e32 v3, v3
	v_exp_f32_e32 v4, v4
	v_exp_f32_e32 v5, v5
	v_exp_f32_e32 v6, v6
	v_exp_f32_e32 v7, v7
	s_cbranch_scc0 .LBB0_510
.LBB0_508:
	v_add_u32_e32 v36, 0xffffff20, v46
	s_nop 0
	v_cmp_gt_i32_e32 vcc, 1, v36
	s_nop 1
	v_cndmask_b32_e32 v0, 0, v0, vcc
	v_cmp_gt_i32_e32 vcc, 0, v36
	s_nop 1
	v_cndmask_b32_e32 v1, 0, v1, vcc
	v_cmp_gt_i32_e32 vcc, -1, v36
	s_nop 1
	v_cndmask_b32_e32 v2, 0, v2, vcc
	v_cmp_gt_i32_e32 vcc, -2, v36
	s_nop 1
	v_cndmask_b32_e32 v3, 0, v3, vcc
	v_cmp_gt_i32_e32 vcc, -15, v36
	s_nop 1
	v_cndmask_b32_e32 v4, 0, v4, vcc
	v_cmp_gt_i32_e32 vcc, -16, v36
	s_nop 1
	v_cndmask_b32_e32 v5, 0, v5, vcc
	v_cmp_gt_i32_e32 vcc, s14, v36
	s_nop 1
	v_cndmask_b32_e32 v6, 0, v6, vcc
	v_cmp_gt_i32_e32 vcc, s15, v36
	s_nop 1
	v_cndmask_b32_e32 v7, 0, v7, vcc
.LBB0_510:
	v_cvt_pk_bf16_f32 v0, v0, v1
	v_cvt_pk_bf16_f32 v1, v2, v3
	v_cvt_pk_bf16_f32 v2, v4, v5
	v_cvt_pk_bf16_f32 v3, v6, v7
	s_add_i32 s2, s66, 0xffffff5f
	s_cmp_gt_i32 s2, s76
	v_mfma_f32_16x16x32_bf16 v[36:39], v[32:35], v[0:3], v[50:53]
	ds_read_b128 v[0:3], v44 offset:24576
	ds_read_b128 v[4:7], v45 offset:24576
	s_nop 0
	ds_read_b128 v[48:51], v44 offset:26624
	ds_read_b128 v[52:55], v45 offset:26624
	s_mov_b64 s[68:69], -1
	s_waitcnt lgkmcnt(3)
	v_mfma_f32_16x16x32_bf16 v[0:3], v[0:3], v[24:27], 0
	s_waitcnt lgkmcnt(2)
	v_mfma_f32_16x16x32_bf16 v[0:3], v[4:7], v[28:31], v[0:3]
	s_waitcnt lgkmcnt(1)
	v_mfma_f32_16x16x32_bf16 v[4:7], v[48:51], v[24:27], 0
	s_waitcnt lgkmcnt(0)
	v_mfma_f32_16x16x32_bf16 v[4:7], v[52:55], v[28:31], v[4:7]
	s_nop 3
	v_fma_f32 v0, v0, s30, 0
	v_fma_f32 v1, v1, s30, 0
	v_fma_f32 v2, v2, s30, 0
	v_fma_f32 v3, v3, s30, 0
	v_exp_f32_e32 v0, v0
	v_fma_f32 v4, v4, s30, 0
	v_fma_f32 v5, v5, s30, 0
	v_fma_f32 v6, v6, s30, 0
	v_fma_f32 v7, v7, s30, 0
	v_exp_f32_e32 v1, v1
	v_exp_f32_e32 v2, v2
	v_exp_f32_e32 v3, v3
	v_exp_f32_e32 v4, v4
	v_exp_f32_e32 v5, v5
	v_exp_f32_e32 v6, v6
	v_exp_f32_e32 v7, v7
	s_cbranch_scc0 .LBB0_487
.LBB0_512:
	v_add_u32_e32 v46, 0xffffff40, v46
	s_nop 0
	v_cmp_gt_i32_e32 vcc, 1, v46
	s_nop 1
	v_cndmask_b32_e32 v0, 0, v0, vcc
	v_cmp_gt_i32_e32 vcc, 0, v46
	s_nop 1
	v_cndmask_b32_e32 v1, 0, v1, vcc
	v_cmp_gt_i32_e32 vcc, -1, v46
	s_nop 1
	v_cndmask_b32_e32 v2, 0, v2, vcc
	v_cmp_gt_i32_e32 vcc, -2, v46
	s_nop 1
	v_cndmask_b32_e32 v3, 0, v3, vcc
	v_cmp_gt_i32_e32 vcc, -15, v46
	s_nop 1
	v_cndmask_b32_e32 v4, 0, v4, vcc
	v_cmp_gt_i32_e32 vcc, -16, v46
	s_nop 1
	v_cndmask_b32_e32 v5, 0, v5, vcc
	v_cmp_gt_i32_e32 vcc, s14, v46
	s_nop 1
	v_cndmask_b32_e32 v6, 0, v6, vcc
	v_cmp_gt_i32_e32 vcc, s15, v46
	s_nop 1
	v_cndmask_b32_e32 v7, 0, v7, vcc
	s_branch .LBB0_487

.LB3_497:
	v_cvt_pk_bf16_f32 v0, v0, v1
	v_cvt_pk_bf16_f32 v1, v2, v3
	v_cvt_pk_bf16_f32 v2, v4, v5
	v_cvt_pk_bf16_f32 v3, v6, v7
	s_add_i32 s2, s66, 0xffffff1f
	s_cmp_gt_i32 s2, s76
	v_mfma_f32_16x16x32_bf16 v[36:39], v[32:35], v[0:3], v[50:53]
	ds_read_b128 v[0:3], v44 offset:12288
	ds_read_b128 v[4:7], v45 offset:12288
	s_nop 0
	ds_read_b128 v[48:51], v44 offset:14336
	ds_read_b128 v[52:55], v45 offset:14336
	s_mov_b64 s[70:71], -1
	s_waitcnt lgkmcnt(3)
	v_mfma_f32_16x16x32_bf16 v[0:3], v[0:3], v[24:27], 0
	s_waitcnt lgkmcnt(2)
	v_mfma_f32_16x16x32_bf16 v[0:3], v[4:7], v[28:31], v[0:3]
	s_waitcnt lgkmcnt(1)
	v_mfma_f32_16x16x32_bf16 v[4:7], v[48:51], v[24:27], 0
	s_waitcnt lgkmcnt(0)
	v_mfma_f32_16x16x32_bf16 v[4:7], v[52:55], v[28:31], v[4:7]
	s_nop 3
	v_fma_f32 v0, v0, s30, 0
	v_fma_f32 v1, v1, s30, 0
	v_fma_f32 v2, v2, s30, 0
	v_fma_f32 v3, v3, s30, 0
	v_exp_f32_e32 v0, v0
	v_fma_f32 v4, v4, s30, 0
	v_fma_f32 v5, v5, s30, 0
	v_fma_f32 v6, v6, s30, 0
	v_fma_f32 v7, v7, s30, 0
	v_exp_f32_e32 v1, v1
	v_exp_f32_e32 v2, v2
	v_exp_f32_e32 v3, v3
	v_exp_f32_e32 v4, v4
	v_exp_f32_e32 v5, v5
	v_exp_f32_e32 v6, v6
	v_exp_f32_e32 v7, v7
	s_cbranch_scc0 .LB3_501

.LB3_506:
	ds_read_b128 v[0:3], v44 offset:20480
	ds_read_b128 v[4:7], v44 offset:22528
	ds_read_b128 v[36:39], v45 offset:20480
	s_add_i32 s2, s66, 0xffffff3f
	s_cmp_gt_i32 s2, s76
	s_mov_b64 s[68:69], -1
	s_waitcnt lgkmcnt(2)
	v_mfma_f32_16x16x32_bf16 v[0:3], v[0:3], v[24:27], 0
	s_waitcnt lgkmcnt(0)
	v_mfma_f32_16x16x32_bf16 v[0:3], v[36:39], v[28:31], v[0:3]
	ds_read_b128 v[36:39], v45 offset:22528
	v_mfma_f32_16x16x32_bf16 v[4:7], v[4:7], v[24:27], 0
	s_waitcnt lgkmcnt(0)
	v_mfma_f32_16x16x32_bf16 v[4:7], v[36:39], v[28:31], v[4:7]
	s_nop 3
	v_fma_f32 v0, v0, s30, 0
	v_fma_f32 v1, v1, s30, 0
	v_fma_f32 v2, v2, s30, 0
	v_fma_f32 v3, v3, s30, 0
	v_fma_f32 v4, v4, s30, 0
	v_fma_f32 v5, v5, s30, 0
	v_fma_f32 v6, v6, s30, 0
	v_fma_f32 v7, v7, s30, 0
	v_exp_f32_e32 v0, v0
	v_exp_f32_e32 v1, v1
	v_exp_f32_e32 v2, v2
	v_exp_f32_e32 v3, v3
	v_exp_f32_e32 v4, v4
	v_exp_f32_e32 v5, v5
	v_exp_f32_e32 v6, v6
	v_exp_f32_e32 v7, v7
	s_cbranch_scc0 .LB3_510

.LB3_510:
	v_cvt_pk_bf16_f32 v0, v0, v1
	v_cvt_pk_bf16_f32 v1, v2, v3
	v_cvt_pk_bf16_f32 v2, v4, v5
	v_cvt_pk_bf16_f32 v3, v6, v7
	s_add_i32 s2, s66, 0xffffff5f
	s_cmp_gt_i32 s2, s76
	v_mfma_f32_16x16x32_bf16 v[36:39], v[32:35], v[0:3], v[50:53]
	ds_read_b128 v[0:3], v44 offset:28672
	ds_read_b128 v[4:7], v45 offset:28672
	s_nop 0
	ds_read_b128 v[48:51], v44 offset:30720
	ds_read_b128 v[52:55], v45 offset:30720
	s_mov_b64 s[68:69], -1
	s_waitcnt lgkmcnt(3)
	v_mfma_f32_16x16x32_bf16 v[0:3], v[0:3], v[24:27], 0
	s_waitcnt lgkmcnt(2)
	v_mfma_f32_16x16x32_bf16 v[0:3], v[4:7], v[28:31], v[0:3]
	s_waitcnt lgkmcnt(1)
	v_mfma_f32_16x16x32_bf16 v[4:7], v[48:51], v[24:27], 0
	s_waitcnt lgkmcnt(0)
	v_mfma_f32_16x16x32_bf16 v[4:7], v[52:55], v[28:31], v[4:7]
	s_nop 3
	v_fma_f32 v0, v0, s30, 0
	v_fma_f32 v1, v1, s30, 0
	v_fma_f32 v2, v2, s30, 0
	v_fma_f32 v3, v3, s30, 0
	v_exp_f32_e32 v0, v0
	v_fma_f32 v4, v4, s30, 0
	v_fma_f32 v5, v5, s30, 0
	v_fma_f32 v6, v6, s30, 0
	v_fma_f32 v7, v7, s30, 0
	v_exp_f32_e32 v1, v1
	v_exp_f32_e32 v2, v2
	v_exp_f32_e32 v3, v3
	v_exp_f32_e32 v4, v4
	v_exp_f32_e32 v5, v5
	v_exp_f32_e32 v6, v6
	v_exp_f32_e32 v7, v7
	s_cbranch_scc0 .LB3_487

.LBB0_525:
	ds_read_b128 v[0:3], v114
	ds_read_b128 v[4:7], v114 offset:2048
	ds_read_b128 v[64:67], v115
	ds_read_b128 v[116:119], v115 offset:2048
	s_add_i32 s2, s67, 31
	s_waitcnt lgkmcnt(3)
	v_mfma_f32_16x16x32_bf16 v[0:3], v[0:3], v[40:43], 0
	s_cmp_gt_i32 s2, s66
	s_mov_b64 s[64:65], -1
	s_waitcnt lgkmcnt(2)
	v_mfma_f32_16x16x32_bf16 v[4:7], v[4:7], v[40:43], 0
	s_waitcnt lgkmcnt(1)
	v_mfma_f32_16x16x32_bf16 v[0:3], v[64:67], v[44:47], v[0:3]
	ds_read_b128 v[64:67], v110 offset:4096
	ds_read_b128 v[68:71], v110 offset:5120
	ds_read_b128 v[72:75], v110 offset:6144
	ds_read_b128 v[76:79], v110 offset:7168
	s_waitcnt lgkmcnt(4)
	v_mfma_f32_16x16x32_bf16 v[4:7], v[116:119], v[44:47], v[4:7]
	s_nop 1
	v_fmamk_f32 v0, v0, 0x3e38aa3b, v111
	v_fmamk_f32 v1, v1, 0x3e38aa3b, v111
	v_fmamk_f32 v2, v2, 0x3e38aa3b, v111
	v_fmamk_f32 v3, v3, 0x3e38aa3b, v111
	v_exp_f32_e32 v0, v0
	s_nop 0
	v_fmamk_f32 v4, v4, 0x3e38aa3b, v111
	v_fmamk_f32 v5, v5, 0x3e38aa3b, v111
	v_fmamk_f32 v6, v6, 0x3e38aa3b, v111
	v_fmamk_f32 v7, v7, 0x3e38aa3b, v111
	v_exp_f32_e32 v1, v1
	v_exp_f32_e32 v2, v2
	v_exp_f32_e32 v3, v3
	v_exp_f32_e32 v4, v4
	v_exp_f32_e32 v5, v5
	v_exp_f32_e32 v6, v6
	v_exp_f32_e32 v7, v7
	s_cbranch_scc0 .LBB0_529
.LBB0_527:
	v_add_u32_e32 v116, s67, v112
	s_nop 0
	v_cmp_gt_i32_e32 vcc, 1, v116
	s_nop 1
	v_cndmask_b32_e32 v0, 0, v0, vcc
	v_cmp_gt_i32_e32 vcc, 0, v116
	s_nop 1
	v_cndmask_b32_e32 v1, 0, v1, vcc
	v_cmp_gt_i32_e32 vcc, -1, v116
	s_nop 1
	v_cndmask_b32_e32 v2, 0, v2, vcc
	v_cmp_gt_i32_e32 vcc, -2, v116
	s_nop 1
	v_cndmask_b32_e32 v3, 0, v3, vcc
	v_cmp_gt_i32_e32 vcc, -15, v116
	s_nop 1
	v_cndmask_b32_e32 v4, 0, v4, vcc
	v_cmp_gt_i32_e32 vcc, -16, v116
	s_nop 1
	v_cndmask_b32_e32 v5, 0, v5, vcc
	v_cmp_gt_i32_e32 vcc, s14, v116
	s_nop 1
	v_cndmask_b32_e32 v6, 0, v6, vcc
	v_cmp_gt_i32_e32 vcc, s15, v116
	s_nop 1
	v_cndmask_b32_e32 v7, 0, v7, vcc

.LBB0_535:
	s_or_b64 exec, exec, s[64:65]
	v_cvt_pk_bf16_f32 v0, v0, v1
	v_cvt_pk_bf16_f32 v1, v2, v3
	v_cvt_pk_bf16_f32 v2, v4, v5
	v_cvt_pk_bf16_f32 v3, v6, v7
	s_add_i32 s2, s67, 63
	s_cmp_gt_i32 s2, s66
	s_waitcnt lgkmcnt(3)
	v_mfma_f32_16x16x32_bf16 v[48:51], v[64:67], v[0:3], v[48:51]
	s_mov_b64 s[64:65], -1
	s_waitcnt lgkmcnt(2)
	v_mfma_f32_16x16x32_bf16 v[56:59], v[68:71], v[0:3], v[56:59]
	s_waitcnt lgkmcnt(1)
	v_mfma_f32_16x16x32_bf16 v[52:55], v[72:75], v[0:3], v[52:55]
	s_waitcnt lgkmcnt(0)
	v_mfma_f32_16x16x32_bf16 v[60:63], v[76:79], v[0:3], v[60:63]
	ds_read_b128 v[0:3], v114 offset:8192
	ds_read_b128 v[4:7], v115 offset:8192
	ds_read_b128 v[118:121], v114 offset:10240
	ds_read_b128 v[122:125], v115 offset:10240
	ds_read_b128 v[72:75], v110 offset:12288
	ds_read_b128 v[76:79], v110 offset:13312
	ds_read_b128 v[68:71], v110 offset:14336
	ds_read_b128 v[64:67], v110 offset:15360
	s_waitcnt lgkmcnt(7)
	v_mfma_f32_16x16x32_bf16 v[0:3], v[0:3], v[40:43], 0
	s_waitcnt lgkmcnt(6)
	v_mfma_f32_16x16x32_bf16 v[0:3], v[4:7], v[44:47], v[0:3]
	s_waitcnt lgkmcnt(5)
	v_mfma_f32_16x16x32_bf16 v[4:7], v[118:121], v[40:43], 0
	s_waitcnt lgkmcnt(4)
	v_mfma_f32_16x16x32_bf16 v[4:7], v[122:125], v[44:47], v[4:7]
	s_nop 3
	v_fmamk_f32 v0, v0, 0x3e38aa3b, v111
	v_fmamk_f32 v1, v1, 0x3e38aa3b, v111
	v_fmamk_f32 v2, v2, 0x3e38aa3b, v111
	v_fmamk_f32 v3, v3, 0x3e38aa3b, v111
	v_exp_f32_e32 v0, v0
	v_fmamk_f32 v4, v4, 0x3e38aa3b, v111
	v_fmamk_f32 v5, v5, 0x3e38aa3b, v111
	v_fmamk_f32 v6, v6, 0x3e38aa3b, v111
	v_fmamk_f32 v7, v7, 0x3e38aa3b, v111
	v_exp_f32_e32 v1, v1
	v_exp_f32_e32 v2, v2
	v_exp_f32_e32 v3, v3
	v_exp_f32_e32 v4, v4
	v_exp_f32_e32 v5, v5
	v_exp_f32_e32 v6, v6
	v_exp_f32_e32 v7, v7
	s_cbranch_scc0 .LBB0_539
.LBB0_537:
	v_add3_u32 v117, v112, s67, 32
	s_nop 0
	v_cmp_gt_i32_e32 vcc, 1, v117
	s_nop 1
	v_cndmask_b32_e32 v0, 0, v0, vcc
	v_cmp_gt_i32_e32 vcc, 0, v117
	s_nop 1
	v_cndmask_b32_e32 v1, 0, v1, vcc
	v_cmp_gt_i32_e32 vcc, -1, v117
	s_nop 1
	v_cndmask_b32_e32 v2, 0, v2, vcc
	v_cmp_gt_i32_e32 vcc, -2, v117
	s_nop 1
	v_cndmask_b32_e32 v3, 0, v3, vcc
	v_cmp_gt_i32_e32 vcc, -15, v117
	s_nop 1
	v_cndmask_b32_e32 v4, 0, v4, vcc
	v_cmp_gt_i32_e32 vcc, -16, v117
	s_nop 1
	v_cndmask_b32_e32 v5, 0, v5, vcc
	v_cmp_gt_i32_e32 vcc, s14, v117
	s_nop 1
	v_cndmask_b32_e32 v6, 0, v6, vcc
	v_cmp_gt_i32_e32 vcc, s15, v117
	s_nop 1
	v_cndmask_b32_e32 v7, 0, v7, vcc

.LBB0_550:
	ds_read_b128 v[0:3], v114 offset:16384
	ds_read_b128 v[4:7], v114 offset:18432
	ds_read_b128 v[64:67], v115 offset:16384
	ds_read_b128 v[118:121], v115 offset:18432
	s_add_i32 s2, s67, 0x5f
	s_waitcnt lgkmcnt(3)
	v_mfma_f32_16x16x32_bf16 v[0:3], v[0:3], v[40:43], 0
	s_cmp_gt_i32 s2, s66
	s_mov_b64 s[62:63], -1
	s_waitcnt lgkmcnt(2)
	v_mfma_f32_16x16x32_bf16 v[4:7], v[4:7], v[40:43], 0
	s_waitcnt lgkmcnt(1)
	v_mfma_f32_16x16x32_bf16 v[0:3], v[64:67], v[44:47], v[0:3]
	ds_read_b128 v[64:67], v110 offset:20480
	ds_read_b128 v[68:71], v110 offset:21504
	ds_read_b128 v[72:75], v110 offset:22528
	ds_read_b128 v[76:79], v110 offset:23552
	s_waitcnt lgkmcnt(4)
	v_mfma_f32_16x16x32_bf16 v[4:7], v[118:121], v[44:47], v[4:7]
	s_nop 1
	v_fmamk_f32 v0, v0, 0x3e38aa3b, v111
	v_fmamk_f32 v1, v1, 0x3e38aa3b, v111
	v_fmamk_f32 v2, v2, 0x3e38aa3b, v111
	v_fmamk_f32 v3, v3, 0x3e38aa3b, v111
	v_exp_f32_e32 v0, v0
	s_nop 0
	v_fmamk_f32 v4, v4, 0x3e38aa3b, v111
	v_fmamk_f32 v5, v5, 0x3e38aa3b, v111
	v_fmamk_f32 v6, v6, 0x3e38aa3b, v111
	v_fmamk_f32 v7, v7, 0x3e38aa3b, v111
	v_exp_f32_e32 v1, v1
	v_exp_f32_e32 v2, v2
	v_exp_f32_e32 v3, v3
	v_exp_f32_e32 v4, v4
	v_exp_f32_e32 v5, v5
	v_exp_f32_e32 v6, v6
	v_exp_f32_e32 v7, v7
	s_cbranch_scc0 .LBB0_554
.LBB0_552:
	v_add3_u32 v117, v112, s67, 64
	s_nop 0
	v_cmp_gt_i32_e32 vcc, 1, v117
	s_nop 1
	v_cndmask_b32_e32 v0, 0, v0, vcc
	v_cmp_gt_i32_e32 vcc, 0, v117
	s_nop 1
	v_cndmask_b32_e32 v1, 0, v1, vcc
	v_cmp_gt_i32_e32 vcc, -1, v117
	s_nop 1
	v_cndmask_b32_e32 v2, 0, v2, vcc
	v_cmp_gt_i32_e32 vcc, -2, v117
	s_nop 1
	v_cndmask_b32_e32 v3, 0, v3, vcc
	v_cmp_gt_i32_e32 vcc, -15, v117
	s_nop 1
	v_cndmask_b32_e32 v4, 0, v4, vcc
	v_cmp_gt_i32_e32 vcc, -16, v117
	s_nop 1
	v_cndmask_b32_e32 v5, 0, v5, vcc
	v_cmp_gt_i32_e32 vcc, s14, v117
	s_nop 1
	v_cndmask_b32_e32 v6, 0, v6, vcc
	v_cmp_gt_i32_e32 vcc, s15, v117
	s_nop 1
	v_cndmask_b32_e32 v7, 0, v7, vcc

.LBB0_560:
	s_or_b64 exec, exec, s[62:63]
	v_cvt_pk_bf16_f32 v0, v0, v1
	v_cvt_pk_bf16_f32 v1, v2, v3
	v_cvt_pk_bf16_f32 v2, v4, v5
	v_cvt_pk_bf16_f32 v3, v6, v7
	s_add_i32 s2, s67, 0x7f
	s_cmp_gt_i32 s2, s66
	s_waitcnt lgkmcnt(3)
	v_mfma_f32_16x16x32_bf16 v[48:51], v[64:67], v[0:3], v[48:51]
	s_mov_b64 s[62:63], -1
	s_waitcnt lgkmcnt(2)
	v_mfma_f32_16x16x32_bf16 v[56:59], v[68:71], v[0:3], v[56:59]
	s_waitcnt lgkmcnt(1)
	v_mfma_f32_16x16x32_bf16 v[52:55], v[72:75], v[0:3], v[52:55]
	s_waitcnt lgkmcnt(0)
	v_mfma_f32_16x16x32_bf16 v[60:63], v[76:79], v[0:3], v[60:63]
	ds_read_b128 v[0:3], v114 offset:24576
	ds_read_b128 v[4:7], v115 offset:24576
	ds_read_b128 v[118:121], v114 offset:26624
	ds_read_b128 v[122:125], v115 offset:26624
	ds_read_b128 v[68:71], v110 offset:28672
	ds_read_b128 v[72:75], v110 offset:29696
	ds_read_b128 v[76:79], v110 offset:30720
	ds_read_b128 v[64:67], v110 offset:31744
	s_waitcnt lgkmcnt(7)
	v_mfma_f32_16x16x32_bf16 v[0:3], v[0:3], v[40:43], 0
	s_waitcnt lgkmcnt(6)
	v_mfma_f32_16x16x32_bf16 v[0:3], v[4:7], v[44:47], v[0:3]
	s_waitcnt lgkmcnt(5)
	v_mfma_f32_16x16x32_bf16 v[4:7], v[118:121], v[40:43], 0
	s_waitcnt lgkmcnt(4)
	v_mfma_f32_16x16x32_bf16 v[4:7], v[122:125], v[44:47], v[4:7]
	s_nop 3
	v_fmamk_f32 v0, v0, 0x3e38aa3b, v111
	v_fmamk_f32 v1, v1, 0x3e38aa3b, v111
	v_fmamk_f32 v2, v2, 0x3e38aa3b, v111
	v_fmamk_f32 v3, v3, 0x3e38aa3b, v111
	v_exp_f32_e32 v0, v0
	v_fmamk_f32 v4, v4, 0x3e38aa3b, v111
	v_fmamk_f32 v5, v5, 0x3e38aa3b, v111
	v_fmamk_f32 v6, v6, 0x3e38aa3b, v111
	v_fmamk_f32 v7, v7, 0x3e38aa3b, v111
	v_exp_f32_e32 v1, v1
	v_exp_f32_e32 v2, v2
	v_exp_f32_e32 v3, v3
	v_exp_f32_e32 v4, v4
	v_exp_f32_e32 v5, v5
	v_exp_f32_e32 v6, v6
	v_exp_f32_e32 v7, v7
	s_cbranch_scc0 .LBB0_564
.LBB0_562:
	v_add_u32_e32 v117, s67, v112
	v_add_u32_e32 v117, 0x60, v117
	s_nop 0
	v_cmp_gt_i32_e32 vcc, 1, v117
	s_nop 1
	v_cndmask_b32_e32 v0, 0, v0, vcc
	v_cmp_gt_i32_e32 vcc, 0, v117
	s_nop 1
	v_cndmask_b32_e32 v1, 0, v1, vcc
	v_cmp_gt_i32_e32 vcc, -1, v117
	s_nop 1
	v_cndmask_b32_e32 v2, 0, v2, vcc
	v_cmp_gt_i32_e32 vcc, -2, v117
	s_nop 1
	v_cndmask_b32_e32 v3, 0, v3, vcc
	v_cmp_gt_i32_e32 vcc, -15, v117
	s_nop 1
	v_cndmask_b32_e32 v4, 0, v4, vcc
	v_cmp_gt_i32_e32 vcc, -16, v117
	s_nop 1
	v_cndmask_b32_e32 v5, 0, v5, vcc
	v_cmp_gt_i32_e32 vcc, s14, v117
	s_nop 1
	v_cndmask_b32_e32 v6, 0, v6, vcc
	v_cmp_gt_i32_e32 vcc, s15, v117
	s_nop 1
	v_cndmask_b32_e32 v7, 0, v7, vcc

.Lsel_have_words:
	v_and_b32_e32 v0, s70, v250
	v_cmp_ne_u32_e64 s[50:51], 0, v0
	v_and_b32_e32 v0, s70, v251
	v_cmp_ne_u32_e64 s[48:49], 0, v0
	v_and_b32_e32 v0, s70, v249
	v_cmp_ne_u32_e64 s[46:47], 0, v0
	v_and_b32_e32 v0, s70, v248
	v_cmp_ne_u32_e64 s[42:43], 0, v0
	s_mov_b64 s[86:87], s[50:51]
	s_mov_b64 s[88:89], s[48:49]
	s_mov_b64 s[90:91], s[46:47]
	s_mov_b64 s[92:93], s[42:43]
	s_or_b64 s[2:3], s[48:49], s[50:51]
	s_or_b64 s[2:3], s[2:3], s[46:47]
	s_or_b64 s[2:3], s[2:3], s[42:43]
	s_cmp_eq_u64 s[2:3], 0
	s_cbranch_scc1 .LBB0_785
	ds_read_b128 v[182:185], v246
	ds_read_b128 v[178:181], v246 offset:2048
	ds_read_b128 v[186:189], v247
	ds_read_b128 v[174:177], v247 offset:2048
	ds_read_b128 v[158:161], v244 offset:4096
	ds_read_b128 v[162:165], v244 offset:5120
	ds_read_b128 v[166:169], v244 offset:6144
	ds_read_b128 v[170:173], v244 offset:7168
	s_add_i32 s2, s28, 0xfffffeff
	s_cmp_le_i32 s2, s26
	s_cselect_b64 s[2:3], -1, 0
	v_cndmask_b32_e64 v0, 0, 1, s[2:3]
	s_cmp_eq_u64 s[50:51], 0
	v_cmp_ne_u32_e64 s[44:45], 1, v0
	s_cbranch_scc1 .LBB0_767
	s_waitcnt lgkmcnt(7)
	v_mfma_f32_16x16x32_bf16 v[0:3], v[182:185], v[104:107], 0
	s_and_b64 vcc, exec, s[44:45]
	s_mov_b64 s[64:65], -1
	s_waitcnt lgkmcnt(6)
	v_mfma_f32_16x16x32_bf16 v[4:7], v[178:181], v[104:107], 0
	s_waitcnt lgkmcnt(5)
	v_mfma_f32_16x16x32_bf16 v[0:3], v[186:189], v[108:111], v[0:3]
	s_waitcnt lgkmcnt(4)
	v_mfma_f32_16x16x32_bf16 v[4:7], v[174:177], v[108:111], v[4:7]
	s_nop 5
	v_exp_f32_e32 v0, v0
	v_exp_f32_e32 v1, v1
	v_exp_f32_e32 v2, v2
	v_exp_f32_e32 v3, v3
	v_exp_f32_e32 v4, v4
	v_exp_f32_e32 v5, v5
	v_exp_f32_e32 v6, v6
	v_exp_f32_e32 v7, v7
	s_cbranch_vccz .LBB0_766
.LBB0_764:
	v_add_u32_e32 v234, s28, v240
	v_add_u32_e32 v234, 0xffffbf20, v234
	s_nop 0
	v_cmp_gt_i32_e32 vcc, 1, v234
	s_nop 1
	v_cndmask_b32_e32 v0, 0, v0, vcc
	v_cmp_gt_i32_e32 vcc, 0, v234
	s_nop 1
	v_cndmask_b32_e32 v1, 0, v1, vcc
	v_cmp_gt_i32_e32 vcc, -1, v234
	s_nop 1
	v_cndmask_b32_e32 v2, 0, v2, vcc
	v_cmp_gt_i32_e32 vcc, -2, v234
	s_nop 1
	v_cndmask_b32_e32 v3, 0, v3, vcc
	v_cmp_gt_i32_e32 vcc, -15, v234
	s_nop 1
	v_cndmask_b32_e32 v4, 0, v4, vcc
	v_cmp_gt_i32_e32 vcc, -16, v234
	s_nop 1
	v_cndmask_b32_e32 v5, 0, v5, vcc
	v_cmp_gt_i32_e32 vcc, s14, v234
	s_nop 1
	v_cndmask_b32_e32 v6, 0, v6, vcc
	v_cmp_gt_i32_e32 vcc, s15, v234
	s_nop 1
	v_cndmask_b32_e32 v7, 0, v7, vcc

.LBB0_767:
	s_cmp_eq_u64 s[48:49], 0
	s_cbranch_scc1 .LBB0_773
	s_waitcnt lgkmcnt(7)
	v_mfma_f32_16x16x32_bf16 v[0:3], v[182:185], v[112:115], 0
	s_and_b64 vcc, exec, s[44:45]
	s_mov_b64 s[50:51], -1
	s_waitcnt lgkmcnt(6)
	v_mfma_f32_16x16x32_bf16 v[4:7], v[178:181], v[112:115], 0
	s_waitcnt lgkmcnt(5)
	v_mfma_f32_16x16x32_bf16 v[0:3], v[186:189], v[116:119], v[0:3]
	s_waitcnt lgkmcnt(4)
	v_mfma_f32_16x16x32_bf16 v[4:7], v[174:177], v[116:119], v[4:7]
	s_nop 5
	v_exp_f32_e32 v0, v0
	v_exp_f32_e32 v1, v1
	v_exp_f32_e32 v2, v2
	v_exp_f32_e32 v3, v3
	v_exp_f32_e32 v4, v4
	v_exp_f32_e32 v5, v5
	v_exp_f32_e32 v6, v6
	v_exp_f32_e32 v7, v7
	s_cbranch_vccz .LBB0_772
.LBB0_770:
	v_add_u32_e32 v234, s28, v240
	v_add_u32_e32 v234, 0xffffbf1c, v234
	s_nop 0
	v_cmp_gt_i32_e32 vcc, 1, v234
	s_nop 1
	v_cndmask_b32_e32 v0, 0, v0, vcc
	v_cmp_gt_i32_e32 vcc, 0, v234
	s_nop 1
	v_cndmask_b32_e32 v1, 0, v1, vcc
	v_cmp_gt_i32_e32 vcc, -1, v234
	s_nop 1
	v_cndmask_b32_e32 v2, 0, v2, vcc
	v_cmp_gt_i32_e32 vcc, -2, v234
	s_nop 1
	v_cndmask_b32_e32 v3, 0, v3, vcc
	v_cmp_gt_i32_e32 vcc, -15, v234
	s_nop 1
	v_cndmask_b32_e32 v4, 0, v4, vcc
	v_cmp_gt_i32_e32 vcc, -16, v234
	s_nop 1
	v_cndmask_b32_e32 v5, 0, v5, vcc
	v_cmp_gt_i32_e32 vcc, s14, v234
	s_nop 1
	v_cndmask_b32_e32 v6, 0, v6, vcc
	v_cmp_gt_i32_e32 vcc, s15, v234
	s_nop 1
	v_cndmask_b32_e32 v7, 0, v7, vcc

.LBB0_773:
	s_cmp_eq_u64 s[46:47], 0
	s_cbranch_scc1 .LBB0_779
	s_waitcnt lgkmcnt(7)
	v_mfma_f32_16x16x32_bf16 v[0:3], v[182:185], v[120:123], 0
	s_and_b64 vcc, exec, s[44:45]
	s_mov_b64 s[48:49], -1
	s_waitcnt lgkmcnt(6)
	v_mfma_f32_16x16x32_bf16 v[4:7], v[178:181], v[120:123], 0
	s_waitcnt lgkmcnt(5)
	v_mfma_f32_16x16x32_bf16 v[0:3], v[186:189], v[124:127], v[0:3]
	s_waitcnt lgkmcnt(4)
	v_mfma_f32_16x16x32_bf16 v[4:7], v[174:177], v[124:127], v[4:7]
	s_nop 5
	v_exp_f32_e32 v0, v0
	v_exp_f32_e32 v1, v1
	v_exp_f32_e32 v2, v2
	v_exp_f32_e32 v3, v3
	v_exp_f32_e32 v4, v4
	v_exp_f32_e32 v5, v5
	v_exp_f32_e32 v6, v6
	v_exp_f32_e32 v7, v7
	s_cbranch_vccz .LBB0_778
.LBB0_776:
	v_add_u32_e32 v234, s28, v240
	v_add_u32_e32 v234, 0xffffbf18, v234
	s_nop 0
	v_cmp_gt_i32_e32 vcc, 1, v234
	s_nop 1
	v_cndmask_b32_e32 v0, 0, v0, vcc
	v_cmp_gt_i32_e32 vcc, 0, v234
	s_nop 1
	v_cndmask_b32_e32 v1, 0, v1, vcc
	v_cmp_gt_i32_e32 vcc, -1, v234
	s_nop 1
	v_cndmask_b32_e32 v2, 0, v2, vcc
	v_cmp_gt_i32_e32 vcc, -2, v234
	s_nop 1
	v_cndmask_b32_e32 v3, 0, v3, vcc
	v_cmp_gt_i32_e32 vcc, -15, v234
	s_nop 1
	v_cndmask_b32_e32 v4, 0, v4, vcc
	v_cmp_gt_i32_e32 vcc, -16, v234
	s_nop 1
	v_cndmask_b32_e32 v5, 0, v5, vcc
	v_cmp_gt_i32_e32 vcc, s14, v234
	s_nop 1
	v_cndmask_b32_e32 v6, 0, v6, vcc
	v_cmp_gt_i32_e32 vcc, s15, v234
	s_nop 1
	v_cndmask_b32_e32 v7, 0, v7, vcc

.LBB0_779:
	s_cmp_eq_u64 s[42:43], 0
	s_cbranch_scc1 .LBB0_785
	s_waitcnt lgkmcnt(7)
	v_mfma_f32_16x16x32_bf16 v[0:3], v[182:185], v[130:133], 0
	s_and_b64 vcc, exec, s[44:45]
	s_mov_b64 s[44:45], -1
	s_waitcnt lgkmcnt(6)
	v_mfma_f32_16x16x32_bf16 v[4:7], v[178:181], v[130:133], 0
	s_waitcnt lgkmcnt(5)
	v_mfma_f32_16x16x32_bf16 v[0:3], v[186:189], v[134:137], v[0:3]
	s_waitcnt lgkmcnt(4)
	v_mfma_f32_16x16x32_bf16 v[4:7], v[174:177], v[134:137], v[4:7]
	s_nop 5
	v_exp_f32_e32 v0, v0
	v_exp_f32_e32 v1, v1
	v_exp_f32_e32 v2, v2
	v_exp_f32_e32 v3, v3
	v_exp_f32_e32 v4, v4
	v_exp_f32_e32 v5, v5
	v_exp_f32_e32 v6, v6
	v_exp_f32_e32 v7, v7
	s_cbranch_vccz .LBB0_784
.LBB0_782:
	v_add_u32_e32 v174, s28, v240
	v_add_u32_e32 v174, 0xffffbf14, v174
	s_nop 0
	v_cmp_gt_i32_e32 vcc, 1, v174
	s_nop 1
	v_cndmask_b32_e32 v0, 0, v0, vcc
	v_cmp_gt_i32_e32 vcc, 0, v174
	s_nop 1
	v_cndmask_b32_e32 v1, 0, v1, vcc
	v_cmp_gt_i32_e32 vcc, -1, v174
	s_nop 1
	v_cndmask_b32_e32 v2, 0, v2, vcc
	v_cmp_gt_i32_e32 vcc, -2, v174
	s_nop 1
	v_cndmask_b32_e32 v3, 0, v3, vcc
	v_cmp_gt_i32_e32 vcc, -15, v174
	s_nop 1
	v_cndmask_b32_e32 v4, 0, v4, vcc
	v_cmp_gt_i32_e32 vcc, -16, v174
	s_nop 1
	v_cndmask_b32_e32 v5, 0, v5, vcc
	v_cmp_gt_i32_e32 vcc, s14, v174
	s_nop 1
	v_cndmask_b32_e32 v6, 0, v6, vcc
	v_cmp_gt_i32_e32 vcc, s15, v174
	s_nop 1
	v_cndmask_b32_e32 v7, 0, v7, vcc

.LBB0_785:
	s_mov_b64 s[50:51], s[86:87]
	s_mov_b64 s[48:49], s[88:89]
	s_mov_b64 s[46:47], s[90:91]
	s_mov_b64 s[42:43], s[92:93]
	s_or_b64 s[2:3], s[48:49], s[50:51]
	s_or_b64 s[2:3], s[2:3], s[46:47]
	s_or_b64 s[2:3], s[2:3], s[42:43]
	s_cmp_eq_u64 s[2:3], 0
	s_cbranch_scc1 .LBB0_810
	ds_read_b128 v[182:185], v246 offset:8192
	ds_read_b128 v[178:181], v246 offset:10240
	ds_read_b128 v[186:189], v247 offset:8192
	ds_read_b128 v[174:177], v247 offset:10240
	ds_read_b128 v[158:161], v244 offset:12288
	ds_read_b128 v[162:165], v244 offset:13312
	ds_read_b128 v[166:169], v244 offset:14336
	ds_read_b128 v[170:173], v244 offset:15360
	s_add_i32 s2, s28, 0xffffff1f
	s_cmp_le_i32 s2, s26
	s_cselect_b64 s[2:3], -1, 0
	v_cndmask_b32_e64 v0, 0, 1, s[2:3]
	s_cmp_eq_u64 s[50:51], 0
	v_cmp_ne_u32_e64 s[44:45], 1, v0
	s_cbranch_scc1 .LBB0_792
	s_waitcnt lgkmcnt(7)
	v_mfma_f32_16x16x32_bf16 v[0:3], v[182:185], v[104:107], 0
	s_and_b64 vcc, exec, s[44:45]
	s_mov_b64 s[64:65], -1
	s_waitcnt lgkmcnt(6)
	v_mfma_f32_16x16x32_bf16 v[4:7], v[178:181], v[104:107], 0
	s_waitcnt lgkmcnt(5)
	v_mfma_f32_16x16x32_bf16 v[0:3], v[186:189], v[108:111], v[0:3]
	s_waitcnt lgkmcnt(4)
	v_mfma_f32_16x16x32_bf16 v[4:7], v[174:177], v[108:111], v[4:7]
	s_nop 5
	v_exp_f32_e32 v0, v0
	v_exp_f32_e32 v1, v1
	v_exp_f32_e32 v2, v2
	v_exp_f32_e32 v3, v3
	v_exp_f32_e32 v4, v4
	v_exp_f32_e32 v5, v5
	v_exp_f32_e32 v6, v6
	v_exp_f32_e32 v7, v7
	s_cbranch_vccz .LBB0_791
.LBB0_789:
	v_add_u32_e32 v234, s28, v240
	v_add_u32_e32 v234, 0xffffbf40, v234
	s_nop 0
	v_cmp_gt_i32_e32 vcc, 1, v234
	s_nop 1
	v_cndmask_b32_e32 v0, 0, v0, vcc
	v_cmp_gt_i32_e32 vcc, 0, v234
	s_nop 1
	v_cndmask_b32_e32 v1, 0, v1, vcc
	v_cmp_gt_i32_e32 vcc, -1, v234
	s_nop 1
	v_cndmask_b32_e32 v2, 0, v2, vcc
	v_cmp_gt_i32_e32 vcc, -2, v234
	s_nop 1
	v_cndmask_b32_e32 v3, 0, v3, vcc
	v_cmp_gt_i32_e32 vcc, -15, v234
	s_nop 1
	v_cndmask_b32_e32 v4, 0, v4, vcc
	v_cmp_gt_i32_e32 vcc, -16, v234
	s_nop 1
	v_cndmask_b32_e32 v5, 0, v5, vcc
	v_cmp_gt_i32_e32 vcc, s14, v234
	s_nop 1
	v_cndmask_b32_e32 v6, 0, v6, vcc
	v_cmp_gt_i32_e32 vcc, s15, v234
	s_nop 1
	v_cndmask_b32_e32 v7, 0, v7, vcc

.LBB0_795:
	v_add_u32_e32 v234, s28, v240
	v_add_u32_e32 v234, 0xffffbf3c, v234
	s_nop 0
	v_cmp_gt_i32_e32 vcc, 1, v234
	s_nop 1
	v_cndmask_b32_e32 v0, 0, v0, vcc
	v_cmp_gt_i32_e32 vcc, 0, v234
	s_nop 1
	v_cndmask_b32_e32 v1, 0, v1, vcc
	v_cmp_gt_i32_e32 vcc, -1, v234
	s_nop 1
	v_cndmask_b32_e32 v2, 0, v2, vcc
	v_cmp_gt_i32_e32 vcc, -2, v234
	s_nop 1
	v_cndmask_b32_e32 v3, 0, v3, vcc
	v_cmp_gt_i32_e32 vcc, -15, v234
	s_nop 1
	v_cndmask_b32_e32 v4, 0, v4, vcc
	v_cmp_gt_i32_e32 vcc, -16, v234
	s_nop 1
	v_cndmask_b32_e32 v5, 0, v5, vcc
	v_cmp_gt_i32_e32 vcc, s14, v234
	s_nop 1
	v_cndmask_b32_e32 v6, 0, v6, vcc
	v_cmp_gt_i32_e32 vcc, s15, v234
	s_nop 1
	v_cndmask_b32_e32 v7, 0, v7, vcc

.LBB0_801:
	v_add_u32_e32 v234, s28, v240
	v_add_u32_e32 v234, 0xffffbf38, v234
	s_nop 0
	v_cmp_gt_i32_e32 vcc, 1, v234
	s_nop 1
	v_cndmask_b32_e32 v0, 0, v0, vcc
	v_cmp_gt_i32_e32 vcc, 0, v234
	s_nop 1
	v_cndmask_b32_e32 v1, 0, v1, vcc
	v_cmp_gt_i32_e32 vcc, -1, v234
	s_nop 1
	v_cndmask_b32_e32 v2, 0, v2, vcc
	v_cmp_gt_i32_e32 vcc, -2, v234
	s_nop 1
	v_cndmask_b32_e32 v3, 0, v3, vcc
	v_cmp_gt_i32_e32 vcc, -15, v234
	s_nop 1
	v_cndmask_b32_e32 v4, 0, v4, vcc
	v_cmp_gt_i32_e32 vcc, -16, v234
	s_nop 1
	v_cndmask_b32_e32 v5, 0, v5, vcc
	v_cmp_gt_i32_e32 vcc, s14, v234
	s_nop 1
	v_cndmask_b32_e32 v6, 0, v6, vcc
	v_cmp_gt_i32_e32 vcc, s15, v234
	s_nop 1
	v_cndmask_b32_e32 v7, 0, v7, vcc

.LBB0_807:
	v_add_u32_e32 v174, s28, v240
	v_add_u32_e32 v174, 0xffffbf34, v174
	s_nop 0
	v_cmp_gt_i32_e32 vcc, 1, v174
	s_nop 1
	v_cndmask_b32_e32 v0, 0, v0, vcc
	v_cmp_gt_i32_e32 vcc, 0, v174
	s_nop 1
	v_cndmask_b32_e32 v1, 0, v1, vcc
	v_cmp_gt_i32_e32 vcc, -1, v174
	s_nop 1
	v_cndmask_b32_e32 v2, 0, v2, vcc
	v_cmp_gt_i32_e32 vcc, -2, v174
	s_nop 1
	v_cndmask_b32_e32 v3, 0, v3, vcc
	v_cmp_gt_i32_e32 vcc, -15, v174
	s_nop 1
	v_cndmask_b32_e32 v4, 0, v4, vcc
	v_cmp_gt_i32_e32 vcc, -16, v174
	s_nop 1
	v_cndmask_b32_e32 v5, 0, v5, vcc
	v_cmp_gt_i32_e32 vcc, s14, v174
	s_nop 1
	v_cndmask_b32_e32 v6, 0, v6, vcc
	v_cmp_gt_i32_e32 vcc, s15, v174
	s_nop 1
	v_cndmask_b32_e32 v7, 0, v7, vcc

.LBB0_815:
	s_add_i32 s2, s27, -3
	s_lshl_b32 s64, 1, s2
	v_and_b32_e32 v0, s64, v250
	v_cmp_ne_u32_e64 s[50:51], 0, v0
	v_and_b32_e32 v0, s64, v251
	v_cmp_ne_u32_e64 s[48:49], 0, v0
	v_and_b32_e32 v0, s64, v249
	v_cmp_ne_u32_e64 s[46:47], 0, v0
	v_and_b32_e32 v0, s64, v248
	v_cmp_ne_u32_e64 s[42:43], 0, v0
	s_mov_b64 s[86:87], s[50:51]
	s_mov_b64 s[88:89], s[48:49]
	s_mov_b64 s[90:91], s[46:47]
	s_mov_b64 s[92:93], s[42:43]
	s_or_b64 s[2:3], s[48:49], s[50:51]
	s_or_b64 s[2:3], s[2:3], s[46:47]
	s_or_b64 s[2:3], s[2:3], s[42:43]
	s_cmp_eq_u64 s[2:3], 0
	s_cbranch_scc1 .LBB0_840
	ds_read_b128 v[182:185], v246 offset:16384
	ds_read_b128 v[178:181], v246 offset:18432
	ds_read_b128 v[186:189], v247 offset:16384
	ds_read_b128 v[174:177], v247 offset:18432
	ds_read_b128 v[158:161], v244 offset:20480
	ds_read_b128 v[162:165], v244 offset:21504
	ds_read_b128 v[166:169], v244 offset:22528
	ds_read_b128 v[170:173], v244 offset:23552
	s_add_i32 s2, s28, 0xffffff3f
	s_cmp_le_i32 s2, s26
	s_cselect_b64 s[2:3], -1, 0
	v_cndmask_b32_e64 v0, 0, 1, s[2:3]
	s_cmp_eq_u64 s[50:51], 0
	v_cmp_ne_u32_e64 s[44:45], 1, v0
	s_cbranch_scc1 .LBB0_822
	s_waitcnt lgkmcnt(7)
	v_mfma_f32_16x16x32_bf16 v[0:3], v[182:185], v[104:107], 0
	s_and_b64 vcc, exec, s[44:45]
	s_mov_b64 s[40:41], -1
	s_waitcnt lgkmcnt(6)
	v_mfma_f32_16x16x32_bf16 v[4:7], v[178:181], v[104:107], 0
	s_waitcnt lgkmcnt(5)
	v_mfma_f32_16x16x32_bf16 v[0:3], v[186:189], v[108:111], v[0:3]
	s_waitcnt lgkmcnt(4)
	v_mfma_f32_16x16x32_bf16 v[4:7], v[174:177], v[108:111], v[4:7]
	s_nop 5
	v_exp_f32_e32 v0, v0
	v_exp_f32_e32 v1, v1
	v_exp_f32_e32 v2, v2
	v_exp_f32_e32 v3, v3
	v_exp_f32_e32 v4, v4
	v_exp_f32_e32 v5, v5
	v_exp_f32_e32 v6, v6
	v_exp_f32_e32 v7, v7
	s_cbranch_vccz .LBB0_821
.LBB0_819:
	v_add_u32_e32 v234, s28, v240
	v_add_u32_e32 v234, 0xffffbf60, v234
	s_nop 0
	v_cmp_gt_i32_e32 vcc, 1, v234
	s_nop 1
	v_cndmask_b32_e32 v0, 0, v0, vcc
	v_cmp_gt_i32_e32 vcc, 0, v234
	s_nop 1
	v_cndmask_b32_e32 v1, 0, v1, vcc
	v_cmp_gt_i32_e32 vcc, -1, v234
	s_nop 1
	v_cndmask_b32_e32 v2, 0, v2, vcc
	v_cmp_gt_i32_e32 vcc, -2, v234
	s_nop 1
	v_cndmask_b32_e32 v3, 0, v3, vcc
	v_cmp_gt_i32_e32 vcc, -15, v234
	s_nop 1
	v_cndmask_b32_e32 v4, 0, v4, vcc
	v_cmp_gt_i32_e32 vcc, -16, v234
	s_nop 1
	v_cndmask_b32_e32 v5, 0, v5, vcc
	v_cmp_gt_i32_e32 vcc, s14, v234
	s_nop 1
	v_cndmask_b32_e32 v6, 0, v6, vcc
	v_cmp_gt_i32_e32 vcc, s15, v234
	s_nop 1
	v_cndmask_b32_e32 v7, 0, v7, vcc

.LBB0_822:
	s_cmp_eq_u64 s[48:49], 0
	s_cbranch_scc1 .LBB0_828
	s_waitcnt lgkmcnt(7)
	v_mfma_f32_16x16x32_bf16 v[0:3], v[182:185], v[112:115], 0
	s_and_b64 vcc, exec, s[44:45]
	s_mov_b64 s[40:41], -1
	s_waitcnt lgkmcnt(6)
	v_mfma_f32_16x16x32_bf16 v[4:7], v[178:181], v[112:115], 0
	s_waitcnt lgkmcnt(5)
	v_mfma_f32_16x16x32_bf16 v[0:3], v[186:189], v[116:119], v[0:3]
	s_waitcnt lgkmcnt(4)
	v_mfma_f32_16x16x32_bf16 v[4:7], v[174:177], v[116:119], v[4:7]
	s_nop 5
	v_exp_f32_e32 v0, v0
	v_exp_f32_e32 v1, v1
	v_exp_f32_e32 v2, v2
	v_exp_f32_e32 v3, v3
	v_exp_f32_e32 v4, v4
	v_exp_f32_e32 v5, v5
	v_exp_f32_e32 v6, v6
	v_exp_f32_e32 v7, v7
	s_cbranch_vccz .LBB0_827
.LBB0_825:
	v_add_u32_e32 v234, s28, v240
	v_add_u32_e32 v234, 0xffffbf5c, v234
	s_nop 0
	v_cmp_gt_i32_e32 vcc, 1, v234
	s_nop 1
	v_cndmask_b32_e32 v0, 0, v0, vcc
	v_cmp_gt_i32_e32 vcc, 0, v234
	s_nop 1
	v_cndmask_b32_e32 v1, 0, v1, vcc
	v_cmp_gt_i32_e32 vcc, -1, v234
	s_nop 1
	v_cndmask_b32_e32 v2, 0, v2, vcc
	v_cmp_gt_i32_e32 vcc, -2, v234
	s_nop 1
	v_cndmask_b32_e32 v3, 0, v3, vcc
	v_cmp_gt_i32_e32 vcc, -15, v234
	s_nop 1
	v_cndmask_b32_e32 v4, 0, v4, vcc
	v_cmp_gt_i32_e32 vcc, -16, v234
	s_nop 1
	v_cndmask_b32_e32 v5, 0, v5, vcc
	v_cmp_gt_i32_e32 vcc, s14, v234
	s_nop 1
	v_cndmask_b32_e32 v6, 0, v6, vcc
	v_cmp_gt_i32_e32 vcc, s15, v234
	s_nop 1
	v_cndmask_b32_e32 v7, 0, v7, vcc

.LBB0_828:
	s_cmp_eq_u64 s[46:47], 0
	s_cbranch_scc1 .LBB0_834
	s_waitcnt lgkmcnt(7)
	v_mfma_f32_16x16x32_bf16 v[0:3], v[182:185], v[120:123], 0
	s_and_b64 vcc, exec, s[44:45]
	s_mov_b64 s[40:41], -1
	s_waitcnt lgkmcnt(6)
	v_mfma_f32_16x16x32_bf16 v[4:7], v[178:181], v[120:123], 0
	s_waitcnt lgkmcnt(5)
	v_mfma_f32_16x16x32_bf16 v[0:3], v[186:189], v[124:127], v[0:3]
	s_waitcnt lgkmcnt(4)
	v_mfma_f32_16x16x32_bf16 v[4:7], v[174:177], v[124:127], v[4:7]
	s_nop 5
	v_exp_f32_e32 v0, v0
	v_exp_f32_e32 v1, v1
	v_exp_f32_e32 v2, v2
	v_exp_f32_e32 v3, v3
	v_exp_f32_e32 v4, v4
	v_exp_f32_e32 v5, v5
	v_exp_f32_e32 v6, v6
	v_exp_f32_e32 v7, v7
	s_cbranch_vccz .LBB0_833
.LBB0_831:
	v_add_u32_e32 v234, s28, v240
	v_add_u32_e32 v234, 0xffffbf58, v234
	s_nop 0
	v_cmp_gt_i32_e32 vcc, 1, v234
	s_nop 1
	v_cndmask_b32_e32 v0, 0, v0, vcc
	v_cmp_gt_i32_e32 vcc, 0, v234
	s_nop 1
	v_cndmask_b32_e32 v1, 0, v1, vcc
	v_cmp_gt_i32_e32 vcc, -1, v234
	s_nop 1
	v_cndmask_b32_e32 v2, 0, v2, vcc
	v_cmp_gt_i32_e32 vcc, -2, v234
	s_nop 1
	v_cndmask_b32_e32 v3, 0, v3, vcc
	v_cmp_gt_i32_e32 vcc, -15, v234
	s_nop 1
	v_cndmask_b32_e32 v4, 0, v4, vcc
	v_cmp_gt_i32_e32 vcc, -16, v234
	s_nop 1
	v_cndmask_b32_e32 v5, 0, v5, vcc
	v_cmp_gt_i32_e32 vcc, s14, v234
	s_nop 1
	v_cndmask_b32_e32 v6, 0, v6, vcc
	v_cmp_gt_i32_e32 vcc, s15, v234
	s_nop 1
	v_cndmask_b32_e32 v7, 0, v7, vcc

.LBB0_834:
	s_cmp_eq_u64 s[42:43], 0
	s_cbranch_scc1 .LBB0_840
	s_waitcnt lgkmcnt(7)
	v_mfma_f32_16x16x32_bf16 v[0:3], v[182:185], v[130:133], 0
	s_and_b64 vcc, exec, s[44:45]
	s_mov_b64 s[40:41], -1
	s_waitcnt lgkmcnt(6)
	v_mfma_f32_16x16x32_bf16 v[4:7], v[178:181], v[130:133], 0
	s_waitcnt lgkmcnt(5)
	v_mfma_f32_16x16x32_bf16 v[0:3], v[186:189], v[134:137], v[0:3]
	s_waitcnt lgkmcnt(4)
	v_mfma_f32_16x16x32_bf16 v[4:7], v[174:177], v[134:137], v[4:7]
	s_nop 5
	v_exp_f32_e32 v0, v0
	v_exp_f32_e32 v1, v1
	v_exp_f32_e32 v2, v2
	v_exp_f32_e32 v3, v3
	v_exp_f32_e32 v4, v4
	v_exp_f32_e32 v5, v5
	v_exp_f32_e32 v6, v6
	v_exp_f32_e32 v7, v7
	s_cbranch_vccz .LBB0_839
.LBB0_837:
	v_add_u32_e32 v174, s28, v240
	v_add_u32_e32 v174, 0xffffbf54, v174
	s_nop 0
	v_cmp_gt_i32_e32 vcc, 1, v174
	s_nop 1
	v_cndmask_b32_e32 v0, 0, v0, vcc
	v_cmp_gt_i32_e32 vcc, 0, v174
	s_nop 1
	v_cndmask_b32_e32 v1, 0, v1, vcc
	v_cmp_gt_i32_e32 vcc, -1, v174
	s_nop 1
	v_cndmask_b32_e32 v2, 0, v2, vcc
	v_cmp_gt_i32_e32 vcc, -2, v174
	s_nop 1
	v_cndmask_b32_e32 v3, 0, v3, vcc
	v_cmp_gt_i32_e32 vcc, -15, v174
	s_nop 1
	v_cndmask_b32_e32 v4, 0, v4, vcc
	v_cmp_gt_i32_e32 vcc, -16, v174
	s_nop 1
	v_cndmask_b32_e32 v5, 0, v5, vcc
	v_cmp_gt_i32_e32 vcc, s14, v174
	s_nop 1
	v_cndmask_b32_e32 v6, 0, v6, vcc
	v_cmp_gt_i32_e32 vcc, s15, v174
	s_nop 1
	v_cndmask_b32_e32 v7, 0, v7, vcc

.LBB0_840:
	s_mov_b64 s[50:51], s[86:87]
	s_mov_b64 s[48:49], s[88:89]
	s_mov_b64 s[46:47], s[90:91]
	s_mov_b64 s[42:43], s[92:93]
	s_or_b64 s[2:3], s[48:49], s[50:51]
	s_or_b64 s[2:3], s[2:3], s[46:47]
	s_or_b64 s[2:3], s[2:3], s[42:43]
	s_cmp_eq_u64 s[2:3], 0
	s_cbranch_scc1 .LBB0_754
	ds_read_b128 v[182:185], v246 offset:24576
	ds_read_b128 v[178:181], v246 offset:26624
	ds_read_b128 v[186:189], v247 offset:24576
	ds_read_b128 v[174:177], v247 offset:26624
	ds_read_b128 v[158:161], v244 offset:28672
	ds_read_b128 v[162:165], v244 offset:29696
	ds_read_b128 v[166:169], v244 offset:30720
	ds_read_b128 v[170:173], v244 offset:31744
	s_add_i32 s2, s28, 0xffffff5f
	s_cmp_le_i32 s2, s26
	s_cselect_b64 s[2:3], -1, 0
	v_cndmask_b32_e64 v0, 0, 1, s[2:3]
	s_cmp_eq_u64 s[50:51], 0
	v_cmp_ne_u32_e64 s[44:45], 1, v0
	s_cbranch_scc1 .LBB0_847
	s_waitcnt lgkmcnt(7)
	v_mfma_f32_16x16x32_bf16 v[0:3], v[182:185], v[104:107], 0
	s_and_b64 vcc, exec, s[44:45]
	s_mov_b64 s[40:41], -1
	s_waitcnt lgkmcnt(6)
	v_mfma_f32_16x16x32_bf16 v[4:7], v[178:181], v[104:107], 0
	s_waitcnt lgkmcnt(5)
	v_mfma_f32_16x16x32_bf16 v[0:3], v[186:189], v[108:111], v[0:3]
	s_waitcnt lgkmcnt(4)
	v_mfma_f32_16x16x32_bf16 v[4:7], v[174:177], v[108:111], v[4:7]
	s_nop 5
	v_exp_f32_e32 v0, v0
	v_exp_f32_e32 v1, v1
	v_exp_f32_e32 v2, v2
	v_exp_f32_e32 v3, v3
	v_exp_f32_e32 v4, v4
	v_exp_f32_e32 v5, v5
	v_exp_f32_e32 v6, v6
	v_exp_f32_e32 v7, v7
	s_cbranch_vccz .LBB0_846
.LBB0_844:
	v_add_u32_e32 v234, s28, v240
	v_add_u32_e32 v234, 0xffffbf80, v234
	s_nop 0
	v_cmp_gt_i32_e32 vcc, 1, v234
	s_nop 1
	v_cndmask_b32_e32 v0, 0, v0, vcc
	v_cmp_gt_i32_e32 vcc, 0, v234
	s_nop 1
	v_cndmask_b32_e32 v1, 0, v1, vcc
	v_cmp_gt_i32_e32 vcc, -1, v234
	s_nop 1
	v_cndmask_b32_e32 v2, 0, v2, vcc
	v_cmp_gt_i32_e32 vcc, -2, v234
	s_nop 1
	v_cndmask_b32_e32 v3, 0, v3, vcc
	v_cmp_gt_i32_e32 vcc, -15, v234
	s_nop 1
	v_cndmask_b32_e32 v4, 0, v4, vcc
	v_cmp_gt_i32_e32 vcc, -16, v234
	s_nop 1
	v_cndmask_b32_e32 v5, 0, v5, vcc
	v_cmp_gt_i32_e32 vcc, s14, v234
	s_nop 1
	v_cndmask_b32_e32 v6, 0, v6, vcc
	v_cmp_gt_i32_e32 vcc, s15, v234
	s_nop 1
	v_cndmask_b32_e32 v7, 0, v7, vcc

.LBB0_850:
	v_add_u32_e32 v234, s28, v240
	v_add_u32_e32 v234, 0xffffbf7c, v234
	s_nop 0
	v_cmp_gt_i32_e32 vcc, 1, v234
	s_nop 1
	v_cndmask_b32_e32 v0, 0, v0, vcc
	v_cmp_gt_i32_e32 vcc, 0, v234
	s_nop 1
	v_cndmask_b32_e32 v1, 0, v1, vcc
	v_cmp_gt_i32_e32 vcc, -1, v234
	s_nop 1
	v_cndmask_b32_e32 v2, 0, v2, vcc
	v_cmp_gt_i32_e32 vcc, -2, v234
	s_nop 1
	v_cndmask_b32_e32 v3, 0, v3, vcc
	v_cmp_gt_i32_e32 vcc, -15, v234
	s_nop 1
	v_cndmask_b32_e32 v4, 0, v4, vcc
	v_cmp_gt_i32_e32 vcc, -16, v234
	s_nop 1
	v_cndmask_b32_e32 v5, 0, v5, vcc
	v_cmp_gt_i32_e32 vcc, s14, v234
	s_nop 1
	v_cndmask_b32_e32 v6, 0, v6, vcc
	v_cmp_gt_i32_e32 vcc, s15, v234
	s_nop 1
	v_cndmask_b32_e32 v7, 0, v7, vcc

.LBB0_856:
	v_add_u32_e32 v234, s28, v240
	v_add_u32_e32 v234, 0xffffbf78, v234
	s_nop 0
	v_cmp_gt_i32_e32 vcc, 1, v234
	s_nop 1
	v_cndmask_b32_e32 v0, 0, v0, vcc
	v_cmp_gt_i32_e32 vcc, 0, v234
	s_nop 1
	v_cndmask_b32_e32 v1, 0, v1, vcc
	v_cmp_gt_i32_e32 vcc, -1, v234
	s_nop 1
	v_cndmask_b32_e32 v2, 0, v2, vcc
	v_cmp_gt_i32_e32 vcc, -2, v234
	s_nop 1
	v_cndmask_b32_e32 v3, 0, v3, vcc
	v_cmp_gt_i32_e32 vcc, -15, v234
	s_nop 1
	v_cndmask_b32_e32 v4, 0, v4, vcc
	v_cmp_gt_i32_e32 vcc, -16, v234
	s_nop 1
	v_cndmask_b32_e32 v5, 0, v5, vcc
	v_cmp_gt_i32_e32 vcc, s14, v234
	s_nop 1
	v_cndmask_b32_e32 v6, 0, v6, vcc
	v_cmp_gt_i32_e32 vcc, s15, v234
	s_nop 1
	v_cndmask_b32_e32 v7, 0, v7, vcc

.LBB0_862:
	v_add_u32_e32 v174, s28, v240
	v_add_u32_e32 v174, 0xffffbf74, v174
	s_nop 0
	v_cmp_gt_i32_e32 vcc, 1, v174
	s_nop 1
	v_cndmask_b32_e32 v0, 0, v0, vcc
	v_cmp_gt_i32_e32 vcc, 0, v174
	s_nop 1
	v_cndmask_b32_e32 v1, 0, v1, vcc
	v_cmp_gt_i32_e32 vcc, -1, v174
	s_nop 1
	v_cndmask_b32_e32 v2, 0, v2, vcc
	v_cmp_gt_i32_e32 vcc, -2, v174
	s_nop 1
	v_cndmask_b32_e32 v3, 0, v3, vcc
	v_cmp_gt_i32_e32 vcc, -15, v174
	s_nop 1
	v_cndmask_b32_e32 v4, 0, v4, vcc
	v_cmp_gt_i32_e32 vcc, -16, v174
	s_nop 1
	v_cndmask_b32_e32 v5, 0, v5, vcc
	v_cmp_gt_i32_e32 vcc, s14, v174
	s_nop 1
	v_cndmask_b32_e32 v6, 0, v6, vcc
	v_cmp_gt_i32_e32 vcc, s15, v174
	s_nop 1
	v_cndmask_b32_e32 v7, 0, v7, vcc
	s_branch .LBB0_753

.Lsel_have_words2:
	v_and_b32_e32 v0, s70, v250
	v_cmp_ne_u32_e64 s[50:51], 0, v0
	v_and_b32_e32 v0, s70, v251
	v_cmp_ne_u32_e64 s[48:49], 0, v0
	v_and_b32_e32 v0, s70, v249
	v_cmp_ne_u32_e64 s[46:47], 0, v0
	v_and_b32_e32 v0, s70, v248
	v_cmp_ne_u32_e64 s[42:43], 0, v0
	s_mov_b64 s[86:87], s[50:51]
	s_mov_b64 s[88:89], s[48:49]
	s_mov_b64 s[90:91], s[46:47]
	s_mov_b64 s[92:93], s[42:43]
	s_or_b64 s[2:3], s[48:49], s[50:51]
	s_or_b64 s[2:3], s[2:3], s[46:47]
	s_or_b64 s[2:3], s[2:3], s[42:43]
	s_cmp_eq_u64 s[2:3], 0
	s_cbranch_scc1 .LB2_785
	ds_read_b128 v[182:185], v246 offset:32768
	ds_read_b128 v[178:181], v246 offset:34816
	ds_read_b128 v[186:189], v247 offset:32768
	ds_read_b128 v[174:177], v247 offset:34816
	ds_read_b128 v[158:161], v244 offset:36864
	ds_read_b128 v[162:165], v244 offset:37888
	ds_read_b128 v[166:169], v244 offset:38912
	ds_read_b128 v[170:173], v244 offset:39936
	s_add_i32 s2, s28, 0xfffffeff
	s_cmp_le_i32 s2, s26
	s_cselect_b64 s[2:3], -1, 0
	v_cndmask_b32_e64 v0, 0, 1, s[2:3]
	s_cmp_eq_u64 s[50:51], 0
	v_cmp_ne_u32_e64 s[44:45], 1, v0
	s_cbranch_scc1 .LB2_767
	s_waitcnt lgkmcnt(7)
	v_mfma_f32_16x16x32_bf16 v[0:3], v[182:185], v[104:107], 0
	s_and_b64 vcc, exec, s[44:45]
	s_mov_b64 s[64:65], -1
	s_waitcnt lgkmcnt(6)
	v_mfma_f32_16x16x32_bf16 v[4:7], v[178:181], v[104:107], 0
	s_waitcnt lgkmcnt(5)
	v_mfma_f32_16x16x32_bf16 v[0:3], v[186:189], v[108:111], v[0:3]
	s_waitcnt lgkmcnt(4)
	v_mfma_f32_16x16x32_bf16 v[4:7], v[174:177], v[108:111], v[4:7]
	s_nop 5
	v_exp_f32_e32 v0, v0
	v_exp_f32_e32 v1, v1
	v_exp_f32_e32 v2, v2
	v_exp_f32_e32 v3, v3
	v_exp_f32_e32 v4, v4
	v_exp_f32_e32 v5, v5
	v_exp_f32_e32 v6, v6
	v_exp_f32_e32 v7, v7
	s_cbranch_vccz .LB2_766

.LB2_785:
	s_mov_b64 s[50:51], s[86:87]
	s_mov_b64 s[48:49], s[88:89]
	s_mov_b64 s[46:47], s[90:91]
	s_mov_b64 s[42:43], s[92:93]
	s_or_b64 s[2:3], s[48:49], s[50:51]
	s_or_b64 s[2:3], s[2:3], s[46:47]
	s_or_b64 s[2:3], s[2:3], s[42:43]
	s_cmp_eq_u64 s[2:3], 0
	s_cbranch_scc1 .LB2_810
	ds_read_b128 v[182:185], v246 offset:40960
	ds_read_b128 v[178:181], v246 offset:43008
	ds_read_b128 v[186:189], v247 offset:40960
	ds_read_b128 v[174:177], v247 offset:43008
	ds_read_b128 v[158:161], v244 offset:45056
	ds_read_b128 v[162:165], v244 offset:46080
	ds_read_b128 v[166:169], v244 offset:47104
	ds_read_b128 v[170:173], v244 offset:48128
	s_add_i32 s2, s28, 0xffffff1f
	s_cmp_le_i32 s2, s26
	s_cselect_b64 s[2:3], -1, 0
	v_cndmask_b32_e64 v0, 0, 1, s[2:3]
	s_cmp_eq_u64 s[50:51], 0
	v_cmp_ne_u32_e64 s[44:45], 1, v0
	s_cbranch_scc1 .LB2_792
	s_waitcnt lgkmcnt(7)
	v_mfma_f32_16x16x32_bf16 v[0:3], v[182:185], v[104:107], 0
	s_and_b64 vcc, exec, s[44:45]
	s_mov_b64 s[64:65], -1
	s_waitcnt lgkmcnt(6)
	v_mfma_f32_16x16x32_bf16 v[4:7], v[178:181], v[104:107], 0
	s_waitcnt lgkmcnt(5)
	v_mfma_f32_16x16x32_bf16 v[0:3], v[186:189], v[108:111], v[0:3]
	s_waitcnt lgkmcnt(4)
	v_mfma_f32_16x16x32_bf16 v[4:7], v[174:177], v[108:111], v[4:7]
	s_nop 5
	v_exp_f32_e32 v0, v0
	v_exp_f32_e32 v1, v1
	v_exp_f32_e32 v2, v2
	v_exp_f32_e32 v3, v3
	v_exp_f32_e32 v4, v4
	v_exp_f32_e32 v5, v5
	v_exp_f32_e32 v6, v6
	v_exp_f32_e32 v7, v7
	s_cbranch_vccz .LB2_791

.LB2_815:
	s_add_i32 s2, s27, -3
	s_lshl_b32 s64, 1, s2
	v_and_b32_e32 v0, s64, v250
	v_cmp_ne_u32_e64 s[50:51], 0, v0
	v_and_b32_e32 v0, s64, v251
	v_cmp_ne_u32_e64 s[48:49], 0, v0
	v_and_b32_e32 v0, s64, v249
	v_cmp_ne_u32_e64 s[46:47], 0, v0
	v_and_b32_e32 v0, s64, v248
	v_cmp_ne_u32_e64 s[42:43], 0, v0
	s_mov_b64 s[86:87], s[50:51]
	s_mov_b64 s[88:89], s[48:49]
	s_mov_b64 s[90:91], s[46:47]
	s_mov_b64 s[92:93], s[42:43]
	s_or_b64 s[2:3], s[48:49], s[50:51]
	s_or_b64 s[2:3], s[2:3], s[46:47]
	s_or_b64 s[2:3], s[2:3], s[42:43]
	s_cmp_eq_u64 s[2:3], 0
	s_cbranch_scc1 .LB2_840
	ds_read_b128 v[182:185], v246 offset:49152
	ds_read_b128 v[178:181], v246 offset:51200
	ds_read_b128 v[186:189], v247 offset:49152
	ds_read_b128 v[174:177], v247 offset:51200
	ds_read_b128 v[158:161], v244 offset:53248
	ds_read_b128 v[162:165], v244 offset:54272
	ds_read_b128 v[166:169], v244 offset:55296
	ds_read_b128 v[170:173], v244 offset:56320
	s_add_i32 s2, s28, 0xffffff3f
	s_cmp_le_i32 s2, s26
	s_cselect_b64 s[2:3], -1, 0
	v_cndmask_b32_e64 v0, 0, 1, s[2:3]
	s_cmp_eq_u64 s[50:51], 0
	v_cmp_ne_u32_e64 s[44:45], 1, v0
	s_cbranch_scc1 .LB2_822
	s_waitcnt lgkmcnt(7)
	v_mfma_f32_16x16x32_bf16 v[0:3], v[182:185], v[104:107], 0
	s_and_b64 vcc, exec, s[44:45]
	s_mov_b64 s[40:41], -1
	s_waitcnt lgkmcnt(6)
	v_mfma_f32_16x16x32_bf16 v[4:7], v[178:181], v[104:107], 0
	s_waitcnt lgkmcnt(5)
	v_mfma_f32_16x16x32_bf16 v[0:3], v[186:189], v[108:111], v[0:3]
	s_waitcnt lgkmcnt(4)
	v_mfma_f32_16x16x32_bf16 v[4:7], v[174:177], v[108:111], v[4:7]
	s_nop 5
	v_exp_f32_e32 v0, v0
	v_exp_f32_e32 v1, v1
	v_exp_f32_e32 v2, v2
	v_exp_f32_e32 v3, v3
	v_exp_f32_e32 v4, v4
	v_exp_f32_e32 v5, v5
	v_exp_f32_e32 v6, v6
	v_exp_f32_e32 v7, v7
	s_cbranch_vccz .LB2_821

.LB2_840:
	s_mov_b64 s[50:51], s[86:87]
	s_mov_b64 s[48:49], s[88:89]
	s_mov_b64 s[46:47], s[90:91]
	s_mov_b64 s[42:43], s[92:93]
	s_or_b64 s[2:3], s[48:49], s[50:51]
	s_or_b64 s[2:3], s[2:3], s[46:47]
	s_or_b64 s[2:3], s[2:3], s[42:43]
	s_cmp_eq_u64 s[2:3], 0
	s_cbranch_scc1 .LB2_754
	ds_read_b128 v[182:185], v246 offset:57344
	ds_read_b128 v[178:181], v246 offset:59392
	ds_read_b128 v[186:189], v247 offset:57344
	ds_read_b128 v[174:177], v247 offset:59392
	ds_read_b128 v[158:161], v244 offset:61440
	ds_read_b128 v[162:165], v244 offset:62464
	ds_read_b128 v[166:169], v244 offset:63488
	ds_read_b128 v[170:173], v244 offset:64512
	s_add_i32 s2, s28, 0xffffff5f
	s_cmp_le_i32 s2, s26
	s_cselect_b64 s[2:3], -1, 0
	v_cndmask_b32_e64 v0, 0, 1, s[2:3]
	s_cmp_eq_u64 s[50:51], 0
	v_cmp_ne_u32_e64 s[44:45], 1, v0
	s_cbranch_scc1 .LB2_847
	s_waitcnt lgkmcnt(7)
	v_mfma_f32_16x16x32_bf16 v[0:3], v[182:185], v[104:107], 0
	s_and_b64 vcc, exec, s[44:45]
	s_mov_b64 s[40:41], -1
	s_waitcnt lgkmcnt(6)
	v_mfma_f32_16x16x32_bf16 v[4:7], v[178:181], v[104:107], 0
	s_waitcnt lgkmcnt(5)
	v_mfma_f32_16x16x32_bf16 v[0:3], v[186:189], v[108:111], v[0:3]
	s_waitcnt lgkmcnt(4)
	v_mfma_f32_16x16x32_bf16 v[4:7], v[174:177], v[108:111], v[4:7]
	s_nop 5
	v_exp_f32_e32 v0, v0
	v_exp_f32_e32 v1, v1
	v_exp_f32_e32 v2, v2
	v_exp_f32_e32 v3, v3
	v_exp_f32_e32 v4, v4
	v_exp_f32_e32 v5, v5
	v_exp_f32_e32 v6, v6
	v_exp_f32_e32 v7, v7
	s_cbranch_vccz .LB2_846
